# fused epilogue: residual-stream stores moved behind the second statistics publish (waves 4-7: right after publishing, waves 0-3: after the exchange) so the publish no longer waits for the store drain
# speedup vs baseline: 1.0143x; 1.0141x over previous
.LBB0_80:
	s_or_b64 exec, exec, s[4:5]
	v_lshlrev_b64 v[232:233], 2, v[224:225]
	s_waitcnt lgkmcnt(0)
	s_barrier
	s_waitcnt lgkmcnt(0)
	v_lshl_add_u64 v[144:145], s[60:61], 0, v[232:233]
	global_load_dwordx4 v[156:159], v[144:145], off
	global_load_dwordx4 v[152:155], v[144:145], off offset:64
	global_load_dwordx4 v[148:151], v[144:145], off offset:512
	s_nop 0
	global_load_dwordx4 v[144:147], v[144:145], off offset:576
	v_lshl_add_u32 v210, v228, 2, 0
	v_add_u32_e32 v249, 0x1000, v210
	ds_read2_b32 v[210:211], v249 offset1:16
	v_add_u32_e32 v228, s17, v228
	v_ashrrev_i32_e32 v229, 31, v228
	v_readlane_b32 s16, v255, 11
	v_readlane_b32 s17, v255, 12
	s_waitcnt lgkmcnt(0)
	v_pk_mul_f32 v[96:97], v[96:97], v[210:211] op_sel_hi:[1,0]
	v_pk_mul_f32 v[98:99], v[98:99], v[210:211] op_sel_hi:[1,0]
	v_pk_mul_f32 v[108:109], v[108:109], v[210:211] op_sel_hi:[1,0]
	v_pk_mul_f32 v[110:111], v[110:111], v[210:211] op_sel_hi:[1,0]
	v_pk_mul_f32 v[104:105], v[104:105], v[210:211] op_sel_hi:[1,0]
	v_pk_mul_f32 v[106:107], v[106:107], v[210:211] op_sel_hi:[1,0]
	v_pk_mul_f32 v[100:101], v[100:101], v[210:211] op_sel_hi:[1,0]
	v_pk_mul_f32 v[102:103], v[102:103], v[210:211] op_sel_hi:[1,0]
	s_andn2_b64 vcc, exec, s[16:17]
	s_waitcnt vmcnt(0)
	v_pk_fma_f32 v[108:109], v[156:157], v[108:109], v[204:205]
	v_lshlrev_b64 v[204:205], 12, v[228:229]
	v_lshl_add_u64 v[204:205], s[30:31], 0, v[204:205]
	v_pk_fma_f32 v[98:99], v[146:147], v[98:99], v[194:195]
	v_pk_fma_f32 v[96:97], v[144:145], v[96:97], v[192:193]
	v_add_u32_e32 v192, 16, v228
	v_mov_b32_e32 v194, v211
	v_ashrrev_i32_e32 v193, 31, v192
	v_pk_mul_f32 v[124:125], v[124:125], v[194:195] op_sel_hi:[1,0]
	v_pk_mul_f32 v[126:127], v[126:127], v[194:195] op_sel_hi:[1,0]
	v_pk_fma_f32 v[124:125], v[156:157], v[124:125], v[188:189]
	v_lshlrev_b64 v[188:189], 12, v[192:193]
	v_lshl_add_u64 v[188:189], s[30:31], 0, v[188:189]
	v_pk_mul_f32 v[120:121], v[120:121], v[194:195] op_sel_hi:[1,0]
	v_pk_mul_f32 v[122:123], v[122:123], v[194:195] op_sel_hi:[1,0]
	v_pk_mul_f32 v[116:117], v[116:117], v[194:195] op_sel_hi:[1,0]
	v_pk_mul_f32 v[118:119], v[118:119], v[194:195] op_sel_hi:[1,0]
	v_pk_mul_f32 v[112:113], v[112:113], v[194:195] op_sel_hi:[1,0]
	v_pk_mul_f32 v[114:115], v[114:115], v[194:195] op_sel_hi:[1,0]
	v_pk_fma_f32 v[110:111], v[158:159], v[110:111], v[206:207]
	v_lshl_add_u64 v[204:205], v[204:205], 0, v[232:233]
	v_pk_fma_f32 v[106:107], v[154:155], v[106:107], v[202:203]
	v_pk_fma_f32 v[104:105], v[152:153], v[104:105], v[200:201]
	v_pk_fma_f32 v[102:103], v[150:151], v[102:103], v[198:199]
	v_pk_fma_f32 v[100:101], v[148:149], v[100:101], v[196:197]
	v_pk_fma_f32 v[126:127], v[158:159], v[126:127], v[190:191]
	v_lshl_add_u64 v[188:189], v[188:189], 0, v[232:233]
	v_pk_fma_f32 v[122:123], v[154:155], v[122:123], v[186:187]
	v_pk_fma_f32 v[120:121], v[152:153], v[120:121], v[184:185]
	v_pk_fma_f32 v[118:119], v[150:151], v[118:119], v[182:183]
	v_pk_fma_f32 v[116:117], v[148:149], v[116:117], v[180:181]
	v_pk_fma_f32 v[114:115], v[146:147], v[114:115], v[178:179]
	v_pk_fma_f32 v[112:113], v[144:145], v[112:113], v[176:177]
	ds_read2_b32 v[178:179], v249 offset0:32 offset1:48
	v_add_u32_e32 v176, 32, v228
	v_ashrrev_i32_e32 v177, 31, v176
	s_waitcnt lgkmcnt(0)
	v_pk_mul_f32 v[80:81], v[80:81], v[178:179] op_sel_hi:[1,0]
	v_pk_mul_f32 v[82:83], v[82:83], v[178:179] op_sel_hi:[1,0]
	v_pk_fma_f32 v[80:81], v[144:145], v[80:81], v[160:161]
	v_pk_fma_f32 v[82:83], v[146:147], v[82:83], v[162:163]
	v_add_u32_e32 v160, 48, v228
	v_mov_b32_e32 v162, v179
	v_pk_mul_f32 v[92:93], v[92:93], v[178:179] op_sel_hi:[1,0]
	v_ashrrev_i32_e32 v161, 31, v160
	v_pk_mul_f32 v[76:77], v[76:77], v[162:163] op_sel_hi:[1,0]
	v_pk_mul_f32 v[64:65], v[64:65], v[162:163] op_sel_hi:[1,0]
	v_pk_fma_f32 v[92:93], v[156:157], v[92:93], v[172:173]
	v_lshlrev_b64 v[172:173], 12, v[176:177]
	v_pk_fma_f32 v[76:77], v[156:157], v[76:77], v[140:141]
	v_lshlrev_b64 v[140:141], 12, v[160:161]
	v_pk_fma_f32 v[64:65], v[144:145], v[64:65], v[128:129]
	v_add_u32_e32 v128, 0x80, v228
	v_pk_mul_f32 v[94:95], v[94:95], v[178:179] op_sel_hi:[1,0]
	v_lshl_add_u64 v[172:173], s[30:31], 0, v[172:173]
	v_pk_mul_f32 v[88:89], v[88:89], v[178:179] op_sel_hi:[1,0]
	v_pk_mul_f32 v[90:91], v[90:91], v[178:179] op_sel_hi:[1,0]
	v_pk_mul_f32 v[84:85], v[84:85], v[178:179] op_sel_hi:[1,0]
	v_pk_mul_f32 v[86:87], v[86:87], v[178:179] op_sel_hi:[1,0]
	v_pk_mul_f32 v[78:79], v[78:79], v[162:163] op_sel_hi:[1,0]
	v_lshl_add_u64 v[140:141], s[30:31], 0, v[140:141]
	v_pk_mul_f32 v[72:73], v[72:73], v[162:163] op_sel_hi:[1,0]
	v_pk_mul_f32 v[74:75], v[74:75], v[162:163] op_sel_hi:[1,0]
	v_pk_mul_f32 v[68:69], v[68:69], v[162:163] op_sel_hi:[1,0]
	v_pk_mul_f32 v[70:71], v[70:71], v[162:163] op_sel_hi:[1,0]
	v_pk_mul_f32 v[66:67], v[66:67], v[162:163] op_sel_hi:[1,0]
	v_ashrrev_i32_e32 v129, 31, v128
	v_pk_fma_f32 v[94:95], v[158:159], v[94:95], v[174:175]
	v_lshl_add_u64 v[172:173], v[172:173], 0, v[232:233]
	v_pk_fma_f32 v[90:91], v[154:155], v[90:91], v[170:171]
	v_pk_fma_f32 v[88:89], v[152:153], v[88:89], v[168:169]
	v_pk_fma_f32 v[86:87], v[150:151], v[86:87], v[166:167]
	v_pk_fma_f32 v[84:85], v[148:149], v[84:85], v[164:165]
	v_pk_fma_f32 v[78:79], v[158:159], v[78:79], v[142:143]
	v_lshl_add_u64 v[140:141], v[140:141], 0, v[232:233]
	v_pk_fma_f32 v[74:75], v[154:155], v[74:75], v[138:139]
	v_pk_fma_f32 v[72:73], v[152:153], v[72:73], v[136:137]
	v_pk_fma_f32 v[70:71], v[150:151], v[70:71], v[134:135]
	v_pk_fma_f32 v[68:69], v[148:149], v[68:69], v[132:133]
	v_pk_fma_f32 v[66:67], v[146:147], v[66:67], v[130:131]
	v_lshlrev_b64 v[130:131], 10, v[128:129]
	v_add_u32_e32 v130, 0x90, v228
	v_add_u32_e32 v132, 0xa0, v228
	v_add_u32_e32 v134, 0xb0, v228
	v_ashrrev_i32_e32 v131, 31, v130
	v_ashrrev_i32_e32 v133, 31, v132
	v_ashrrev_i32_e32 v135, 31, v134
	v_lshlrev_b64 v[162:163], 12, v[128:129]
	v_lshl_add_u64 v[162:163], v[230:231], 0, v[162:163]
	global_load_dwordx4 v[164:167], v[162:163], off
	global_load_dwordx4 v[168:171], v[162:163], off offset:64
	global_load_dwordx4 v[172:175], v[162:163], off offset:512
	global_load_dwordx4 v[180:183], v[162:163], off offset:576
	v_lshlrev_b64 v[162:163], 12, v[130:131]
	v_lshl_add_u64 v[162:163], v[230:231], 0, v[162:163]
	global_load_dwordx4 v[184:187], v[162:163], off
	global_load_dwordx4 v[188:191], v[162:163], off offset:64
	global_load_dwordx4 v[196:199], v[162:163], off offset:512
	global_load_dwordx4 v[200:203], v[162:163], off offset:576
	v_lshlrev_b64 v[162:163], 12, v[132:133]
	v_lshl_add_u64 v[162:163], v[230:231], 0, v[162:163]
	global_load_dwordx4 v[204:207], v[162:163], off
	global_load_dwordx4 v[136:139], v[162:163], off offset:64
	global_load_dwordx4 v[140:143], v[162:163], off offset:512
	global_load_dwordx4 v[210:213], v[162:163], off offset:576
	ds_read2_b32 v[194:195], v249 offset0:128 offset1:144
	ds_read2_b32 v[178:179], v249 offset0:160 offset1:176
	s_waitcnt lgkmcnt(0)
	v_pk_mul_f32 v[60:61], v[60:61], v[194:195] op_sel_hi:[1,0]
	v_pk_mul_f32 v[62:63], v[62:63], v[194:195] op_sel_hi:[1,0]
	v_pk_mul_f32 v[56:57], v[56:57], v[194:195] op_sel_hi:[1,0]
	v_pk_mul_f32 v[58:59], v[58:59], v[194:195] op_sel_hi:[1,0]
	v_pk_mul_f32 v[52:53], v[52:53], v[194:195] op_sel_hi:[1,0]
	v_pk_mul_f32 v[54:55], v[54:55], v[194:195] op_sel_hi:[1,0]
	v_pk_mul_f32 v[48:49], v[48:49], v[194:195] op_sel_hi:[1,0]
	v_pk_mul_f32 v[50:51], v[50:51], v[194:195] op_sel_hi:[1,0]
	v_mov_b32_e32 v194, v195
	v_pk_mul_f32 v[44:45], v[44:45], v[194:195] op_sel_hi:[1,0]
	v_pk_mul_f32 v[46:47], v[46:47], v[194:195] op_sel_hi:[1,0]
	v_pk_mul_f32 v[40:41], v[40:41], v[194:195] op_sel_hi:[1,0]
	v_pk_mul_f32 v[42:43], v[42:43], v[194:195] op_sel_hi:[1,0]
	v_pk_mul_f32 v[36:37], v[36:37], v[194:195] op_sel_hi:[1,0]
	v_pk_mul_f32 v[38:39], v[38:39], v[194:195] op_sel_hi:[1,0]
	v_pk_mul_f32 v[32:33], v[32:33], v[194:195] op_sel_hi:[1,0]
	v_pk_mul_f32 v[34:35], v[34:35], v[194:195] op_sel_hi:[1,0]
	v_pk_mul_f32 v[28:29], v[28:29], v[178:179] op_sel_hi:[1,0]
	v_pk_mul_f32 v[30:31], v[30:31], v[178:179] op_sel_hi:[1,0]
	v_pk_mul_f32 v[24:25], v[24:25], v[178:179] op_sel_hi:[1,0]
	v_pk_mul_f32 v[26:27], v[26:27], v[178:179] op_sel_hi:[1,0]
	v_pk_mul_f32 v[20:21], v[20:21], v[178:179] op_sel_hi:[1,0]
	v_pk_mul_f32 v[22:23], v[22:23], v[178:179] op_sel_hi:[1,0]
	v_pk_mul_f32 v[16:17], v[16:17], v[178:179] op_sel_hi:[1,0]
	v_pk_mul_f32 v[18:19], v[18:19], v[178:179] op_sel_hi:[1,0]
	v_mov_b32_e32 v178, v179
	v_pk_mul_f32 v[12:13], v[12:13], v[178:179] op_sel_hi:[1,0]
	v_pk_mul_f32 v[14:15], v[14:15], v[178:179] op_sel_hi:[1,0]
	v_pk_mul_f32 v[8:9], v[8:9], v[178:179] op_sel_hi:[1,0]
	v_pk_mul_f32 v[10:11], v[10:11], v[178:179] op_sel_hi:[1,0]
	v_pk_mul_f32 v[4:5], v[4:5], v[178:179] op_sel_hi:[1,0]
	v_pk_mul_f32 v[6:7], v[6:7], v[178:179] op_sel_hi:[1,0]
	v_pk_mul_f32 v[0:1], v[0:1], v[178:179] op_sel_hi:[1,0]
	v_pk_mul_f32 v[2:3], v[2:3], v[178:179] op_sel_hi:[1,0]
	s_waitcnt vmcnt(11)
	v_pk_fma_f32 v[60:61], v[156:157], v[60:61], v[164:165]
	v_pk_fma_f32 v[62:63], v[158:159], v[62:63], v[166:167]
	s_waitcnt vmcnt(10)
	v_pk_fma_f32 v[56:57], v[152:153], v[56:57], v[168:169]
	v_pk_fma_f32 v[58:59], v[154:155], v[58:59], v[170:171]
	s_waitcnt vmcnt(9)
	v_pk_fma_f32 v[52:53], v[148:149], v[52:53], v[172:173]
	v_pk_fma_f32 v[54:55], v[150:151], v[54:55], v[174:175]
	s_waitcnt vmcnt(8)
	v_pk_fma_f32 v[48:49], v[144:145], v[48:49], v[180:181]
	v_pk_fma_f32 v[50:51], v[146:147], v[50:51], v[182:183]
	v_lshlrev_b64 v[162:163], 12, v[134:135]
	v_lshl_add_u64 v[162:163], v[230:231], 0, v[162:163]
	global_load_dwordx4 v[164:167], v[162:163], off
	global_load_dwordx4 v[168:171], v[162:163], off offset:64
	global_load_dwordx4 v[172:175], v[162:163], off offset:512
	global_load_dwordx4 v[180:183], v[162:163], off offset:576
	s_waitcnt vmcnt(11)
	v_pk_fma_f32 v[44:45], v[156:157], v[44:45], v[184:185]
	v_pk_fma_f32 v[46:47], v[158:159], v[46:47], v[186:187]
	s_waitcnt vmcnt(10)
	v_pk_fma_f32 v[40:41], v[152:153], v[40:41], v[188:189]
	v_pk_fma_f32 v[42:43], v[154:155], v[42:43], v[190:191]
	s_waitcnt vmcnt(9)
	v_pk_fma_f32 v[36:37], v[148:149], v[36:37], v[196:197]
	v_pk_fma_f32 v[38:39], v[150:151], v[38:39], v[198:199]
	s_waitcnt vmcnt(8)
	v_pk_fma_f32 v[32:33], v[144:145], v[32:33], v[200:201]
	v_pk_fma_f32 v[34:35], v[146:147], v[34:35], v[202:203]
	s_waitcnt vmcnt(7)
	v_pk_fma_f32 v[28:29], v[156:157], v[28:29], v[204:205]
	v_pk_fma_f32 v[30:31], v[158:159], v[30:31], v[206:207]
	s_waitcnt vmcnt(6)
	v_pk_fma_f32 v[24:25], v[152:153], v[24:25], v[136:137]
	v_pk_fma_f32 v[26:27], v[154:155], v[26:27], v[138:139]
	s_waitcnt vmcnt(5)
	v_pk_fma_f32 v[20:21], v[148:149], v[20:21], v[140:141]
	v_pk_fma_f32 v[22:23], v[150:151], v[22:23], v[142:143]
	s_waitcnt vmcnt(4)
	v_pk_fma_f32 v[16:17], v[144:145], v[16:17], v[210:211]
	v_pk_fma_f32 v[18:19], v[146:147], v[18:19], v[212:213]
	s_waitcnt vmcnt(3)
	v_pk_fma_f32 v[12:13], v[156:157], v[12:13], v[164:165]
	v_pk_fma_f32 v[14:15], v[158:159], v[14:15], v[166:167]
	s_waitcnt vmcnt(2)
	v_pk_fma_f32 v[8:9], v[152:153], v[8:9], v[168:169]
	v_pk_fma_f32 v[10:11], v[154:155], v[10:11], v[170:171]
	s_waitcnt vmcnt(1)
	v_pk_fma_f32 v[4:5], v[148:149], v[4:5], v[172:173]
	v_pk_fma_f32 v[6:7], v[150:151], v[6:7], v[174:175]
	s_waitcnt vmcnt(0)
	v_pk_fma_f32 v[0:1], v[144:145], v[0:1], v[180:181]
	v_pk_fma_f32 v[2:3], v[146:147], v[2:3], v[182:183]
	s_cbranch_vccz .Lepi2_st2_1
	v_mov_b32_e32 v138, v228
	v_ashrrev_i32_e32 v139, 31, v138
	v_lshlrev_b64 v[138:139], 12, v[138:139]
	v_lshl_add_u64 v[138:139], s[30:31], 0, v[138:139]
	v_lshl_add_u64 v[138:139], v[138:139], 0, v[232:233]
	global_store_dwordx4 v[138:139], v[108:111], off
	global_store_dwordx4 v[138:139], v[104:107], off offset:64
	global_store_dwordx4 v[138:139], v[100:103], off offset:512
	global_store_dwordx4 v[138:139], v[96:99], off offset:576
	s_nop 1
	v_add_u32_e32 v138, 0x10, v228
	v_ashrrev_i32_e32 v139, 31, v138
	v_lshlrev_b64 v[138:139], 12, v[138:139]
	v_lshl_add_u64 v[138:139], s[30:31], 0, v[138:139]
	v_lshl_add_u64 v[138:139], v[138:139], 0, v[232:233]
	global_store_dwordx4 v[138:139], v[124:127], off
	global_store_dwordx4 v[138:139], v[120:123], off offset:64
	global_store_dwordx4 v[138:139], v[116:119], off offset:512
	global_store_dwordx4 v[138:139], v[112:115], off offset:576
	s_nop 1
	v_add_u32_e32 v138, 0x20, v228
	v_ashrrev_i32_e32 v139, 31, v138
	v_lshlrev_b64 v[138:139], 12, v[138:139]
	v_lshl_add_u64 v[138:139], s[30:31], 0, v[138:139]
	v_lshl_add_u64 v[138:139], v[138:139], 0, v[232:233]
	global_store_dwordx4 v[138:139], v[92:95], off
	global_store_dwordx4 v[138:139], v[88:91], off offset:64
	global_store_dwordx4 v[138:139], v[84:87], off offset:512
	global_store_dwordx4 v[138:139], v[80:83], off offset:576
	s_nop 1
	v_add_u32_e32 v138, 0x30, v228
	v_ashrrev_i32_e32 v139, 31, v138
	v_lshlrev_b64 v[138:139], 12, v[138:139]
	v_lshl_add_u64 v[138:139], s[30:31], 0, v[138:139]
	v_lshl_add_u64 v[138:139], v[138:139], 0, v[232:233]
	global_store_dwordx4 v[138:139], v[76:79], off
	global_store_dwordx4 v[138:139], v[72:75], off offset:64
	global_store_dwordx4 v[138:139], v[68:71], off offset:512
	global_store_dwordx4 v[138:139], v[64:67], off offset:576
	s_nop 1
	v_add_u32_e32 v138, 0x80, v228
	v_ashrrev_i32_e32 v139, 31, v138
	v_lshlrev_b64 v[138:139], 12, v[138:139]
	v_lshl_add_u64 v[138:139], s[30:31], 0, v[138:139]
	v_lshl_add_u64 v[138:139], v[138:139], 0, v[232:233]
	global_store_dwordx4 v[138:139], v[60:63], off
	global_store_dwordx4 v[138:139], v[56:59], off offset:64
	global_store_dwordx4 v[138:139], v[52:55], off offset:512
	global_store_dwordx4 v[138:139], v[48:51], off offset:576
	s_nop 1
	v_add_u32_e32 v138, 0x90, v228
	v_ashrrev_i32_e32 v139, 31, v138
	v_lshlrev_b64 v[138:139], 12, v[138:139]
	v_lshl_add_u64 v[138:139], s[30:31], 0, v[138:139]
	v_lshl_add_u64 v[138:139], v[138:139], 0, v[232:233]
	global_store_dwordx4 v[138:139], v[44:47], off
	global_store_dwordx4 v[138:139], v[40:43], off offset:64
	global_store_dwordx4 v[138:139], v[36:39], off offset:512
	global_store_dwordx4 v[138:139], v[32:35], off offset:576
	s_nop 1
	v_add_u32_e32 v138, 0xa0, v228
	v_ashrrev_i32_e32 v139, 31, v138
	v_lshlrev_b64 v[138:139], 12, v[138:139]
	v_lshl_add_u64 v[138:139], s[30:31], 0, v[138:139]
	v_lshl_add_u64 v[138:139], v[138:139], 0, v[232:233]
	global_store_dwordx4 v[138:139], v[28:31], off
	global_store_dwordx4 v[138:139], v[24:27], off offset:64
	global_store_dwordx4 v[138:139], v[20:23], off offset:512
	global_store_dwordx4 v[138:139], v[16:19], off offset:576
	s_nop 1
	v_add_u32_e32 v138, 0xb0, v228
	v_ashrrev_i32_e32 v139, 31, v138
	v_lshlrev_b64 v[138:139], 12, v[138:139]
	v_lshl_add_u64 v[138:139], s[30:31], 0, v[138:139]
	v_lshl_add_u64 v[138:139], v[138:139], 0, v[232:233]
	global_store_dwordx4 v[138:139], v[12:15], off
	global_store_dwordx4 v[138:139], v[8:11], off offset:64
	global_store_dwordx4 v[138:139], v[4:7], off offset:512
	global_store_dwordx4 v[138:139], v[0:3], off offset:576
	s_nop 1
	s_branch .LBB0_115
.Lepi2_st2_1:
	v_mul_f32_e32 v136, v109, v109
	v_mul_f32_e32 v137, v111, v111
	v_fmac_f32_e32 v136, v108, v108
	v_fmac_f32_e32 v137, v110, v110
	v_add_f32_e32 v136, v136, v137
	v_mul_f32_e32 v137, v105, v105
	v_mul_f32_e32 v138, v107, v107
	v_fmac_f32_e32 v137, v104, v104
	v_fmac_f32_e32 v138, v106, v106
	v_add_f32_e32 v137, v137, v138
	v_add_f32_e32 v136, v136, v137
	v_mul_f32_e32 v137, v101, v101
	v_mul_f32_e32 v138, v103, v103
	v_fmac_f32_e32 v137, v100, v100
	v_fmac_f32_e32 v138, v102, v102
	v_add_f32_e32 v137, v137, v138
	v_add_f32_e32 v136, v137, v136
	v_mul_f32_e32 v137, v97, v97
	v_mul_f32_e32 v138, v99, v99
	v_fmac_f32_e32 v137, v96, v96
	v_fmac_f32_e32 v138, v98, v98
	v_add_f32_e32 v137, v137, v138
	v_add_f32_e32 v136, v137, v136
	ds_bpermute_b32 v137, v208, v136
	s_waitcnt lgkmcnt(0)
	v_add_f32_e32 v136, v136, v137
	ds_bpermute_b32 v137, v248, v136
	s_and_saveexec_b64 s[4:5], s[8:9]
	s_cbranch_execz .LBB0_83
	s_lshl_b32 s14, s66, 10
	s_add_i32 s14, s36, s14
	v_lshl_add_u32 v138, v221, 4, s14
	s_waitcnt lgkmcnt(0)
	v_add_f32_e32 v136, v136, v137
	ds_write_b32 v138, v136

.LBB0_102:
	s_or_b64 exec, exec, s[4:5]
	v_readfirstlane_b32 vcc_lo, v222
	s_lshr_b32 vcc_lo, vcc_lo, 6
	s_cmp_lt_u32 vcc_lo, 4
	s_cbranch_scc1 .Lepi2_nost_1
	v_mov_b32_e32 v138, v228
	v_ashrrev_i32_e32 v139, 31, v138
	v_lshlrev_b64 v[138:139], 12, v[138:139]
	v_lshl_add_u64 v[138:139], s[30:31], 0, v[138:139]
	v_lshl_add_u64 v[138:139], v[138:139], 0, v[232:233]
	global_store_dwordx4 v[138:139], v[108:111], off
	global_store_dwordx4 v[138:139], v[104:107], off offset:64
	global_store_dwordx4 v[138:139], v[100:103], off offset:512
	global_store_dwordx4 v[138:139], v[96:99], off offset:576
	s_nop 1
	v_add_u32_e32 v138, 0x10, v228
	v_ashrrev_i32_e32 v139, 31, v138
	v_lshlrev_b64 v[138:139], 12, v[138:139]
	v_lshl_add_u64 v[138:139], s[30:31], 0, v[138:139]
	v_lshl_add_u64 v[138:139], v[138:139], 0, v[232:233]
	global_store_dwordx4 v[138:139], v[124:127], off
	global_store_dwordx4 v[138:139], v[120:123], off offset:64
	global_store_dwordx4 v[138:139], v[116:119], off offset:512
	global_store_dwordx4 v[138:139], v[112:115], off offset:576
	s_nop 1
	v_add_u32_e32 v138, 0x20, v228
	v_ashrrev_i32_e32 v139, 31, v138
	v_lshlrev_b64 v[138:139], 12, v[138:139]
	v_lshl_add_u64 v[138:139], s[30:31], 0, v[138:139]
	v_lshl_add_u64 v[138:139], v[138:139], 0, v[232:233]
	global_store_dwordx4 v[138:139], v[92:95], off
	global_store_dwordx4 v[138:139], v[88:91], off offset:64
	global_store_dwordx4 v[138:139], v[84:87], off offset:512
	global_store_dwordx4 v[138:139], v[80:83], off offset:576
	s_nop 1
	v_add_u32_e32 v138, 0x30, v228
	v_ashrrev_i32_e32 v139, 31, v138
	v_lshlrev_b64 v[138:139], 12, v[138:139]
	v_lshl_add_u64 v[138:139], s[30:31], 0, v[138:139]
	v_lshl_add_u64 v[138:139], v[138:139], 0, v[232:233]
	global_store_dwordx4 v[138:139], v[76:79], off
	global_store_dwordx4 v[138:139], v[72:75], off offset:64
	global_store_dwordx4 v[138:139], v[68:71], off offset:512
	global_store_dwordx4 v[138:139], v[64:67], off offset:576
	s_nop 1
	v_add_u32_e32 v138, 0x80, v228
	v_ashrrev_i32_e32 v139, 31, v138
	v_lshlrev_b64 v[138:139], 12, v[138:139]
	v_lshl_add_u64 v[138:139], s[30:31], 0, v[138:139]
	v_lshl_add_u64 v[138:139], v[138:139], 0, v[232:233]
	global_store_dwordx4 v[138:139], v[60:63], off
	global_store_dwordx4 v[138:139], v[56:59], off offset:64
	global_store_dwordx4 v[138:139], v[52:55], off offset:512
	global_store_dwordx4 v[138:139], v[48:51], off offset:576
	s_nop 1
	v_add_u32_e32 v138, 0x90, v228
	v_ashrrev_i32_e32 v139, 31, v138
	v_lshlrev_b64 v[138:139], 12, v[138:139]
	v_lshl_add_u64 v[138:139], s[30:31], 0, v[138:139]
	v_lshl_add_u64 v[138:139], v[138:139], 0, v[232:233]
	global_store_dwordx4 v[138:139], v[44:47], off
	global_store_dwordx4 v[138:139], v[40:43], off offset:64
	global_store_dwordx4 v[138:139], v[36:39], off offset:512
	global_store_dwordx4 v[138:139], v[32:35], off offset:576
	s_nop 1
	v_add_u32_e32 v138, 0xa0, v228
	v_ashrrev_i32_e32 v139, 31, v138
	v_lshlrev_b64 v[138:139], 12, v[138:139]
	v_lshl_add_u64 v[138:139], s[30:31], 0, v[138:139]
	v_lshl_add_u64 v[138:139], v[138:139], 0, v[232:233]
	global_store_dwordx4 v[138:139], v[28:31], off
	global_store_dwordx4 v[138:139], v[24:27], off offset:64
	global_store_dwordx4 v[138:139], v[20:23], off offset:512
	global_store_dwordx4 v[138:139], v[16:19], off offset:576
	s_nop 1
	v_add_u32_e32 v138, 0xb0, v228
	v_ashrrev_i32_e32 v139, 31, v138
	v_lshlrev_b64 v[138:139], 12, v[138:139]
	v_lshl_add_u64 v[138:139], s[30:31], 0, v[138:139]
	v_lshl_add_u64 v[138:139], v[138:139], 0, v[232:233]
	global_store_dwordx4 v[138:139], v[12:15], off
	global_store_dwordx4 v[138:139], v[8:11], off offset:64
	global_store_dwordx4 v[138:139], v[4:7], off offset:512
	global_store_dwordx4 v[138:139], v[0:3], off offset:576
	s_nop 1
.Lepi2_nost_1:
	s_andn2_b64 vcc, exec, s[58:59]
	s_cbranch_vccnz .LBB0_112
	s_lshl_b32 s4, s89, 6
	s_ashr_i32 s5, s4, 31
	s_lshl_b64 s[4:5], s[4:5], 2
	s_add_u32 s4, s33, s4
	s_addc_u32 s5, s21, s5
	s_mov_b32 s12, 0x400001
	s_branch .LBB0_105

.LBB0_112:
	s_waitcnt lgkmcnt(0)
	s_barrier
	s_and_saveexec_b64 s[4:5], s[10:11]
	s_cbranch_execz .LBB0_114
	s_waitcnt lgkmcnt(0)
	v_lshl_add_u64 v[136:137], v[226:227], 4, s[40:41]
	global_load_dword v138, v[136:137], off sc1
	global_load_dword v139, v[136:137], off offset:4 sc1
	global_load_dword v140, v[136:137], off offset:8 sc1
	global_load_dword v141, v[136:137], off offset:12 sc1
	s_waitcnt vmcnt(0)
	v_add_f32_e32 v138, 0, v138
	v_add_f32_e32 v138, v138, v139
	v_add_f32_e32 v138, v138, v140
	v_add_f32_e32 v136, v138, v141
	v_fmamk_f32 v136, v136, 0x3a800000, v236
	v_cmp_gt_f32_e32 vcc, s3, v136
	v_mul_f32_e32 v137, 0x4b800000, v136
	s_nop 0
	v_cndmask_b32_e32 v136, v136, v137, vcc
	v_rsq_f32_e32 v136, v136
	s_nop 0
	v_mul_f32_e32 v137, 0x45800000, v136
	v_cndmask_b32_e32 v136, v136, v137, vcc
	v_lshl_add_u32 v137, v250, 2, 0
	ds_write_b32 v137, v136 offset:4096
.LBB0_114:
	s_or_b64 exec, exec, s[4:5]
	s_waitcnt lgkmcnt(0)
	s_barrier
	v_readfirstlane_b32 vcc_lo, v222
	s_lshr_b32 vcc_lo, vcc_lo, 6
	s_cmp_gt_u32 vcc_lo, 3
	s_cbranch_scc1 .Lepi2_nost2_1
	v_mov_b32_e32 v138, v228
	v_ashrrev_i32_e32 v139, 31, v138
	v_lshlrev_b64 v[138:139], 12, v[138:139]
	v_lshl_add_u64 v[138:139], s[30:31], 0, v[138:139]
	v_lshl_add_u64 v[138:139], v[138:139], 0, v[232:233]
	global_store_dwordx4 v[138:139], v[108:111], off
	global_store_dwordx4 v[138:139], v[104:107], off offset:64
	global_store_dwordx4 v[138:139], v[100:103], off offset:512
	global_store_dwordx4 v[138:139], v[96:99], off offset:576
	s_nop 1
	v_add_u32_e32 v138, 0x10, v228
	v_ashrrev_i32_e32 v139, 31, v138
	v_lshlrev_b64 v[138:139], 12, v[138:139]
	v_lshl_add_u64 v[138:139], s[30:31], 0, v[138:139]
	v_lshl_add_u64 v[138:139], v[138:139], 0, v[232:233]
	global_store_dwordx4 v[138:139], v[124:127], off
	global_store_dwordx4 v[138:139], v[120:123], off offset:64
	global_store_dwordx4 v[138:139], v[116:119], off offset:512
	global_store_dwordx4 v[138:139], v[112:115], off offset:576
	s_nop 1
	v_add_u32_e32 v138, 0x20, v228
	v_ashrrev_i32_e32 v139, 31, v138
	v_lshlrev_b64 v[138:139], 12, v[138:139]
	v_lshl_add_u64 v[138:139], s[30:31], 0, v[138:139]
	v_lshl_add_u64 v[138:139], v[138:139], 0, v[232:233]
	global_store_dwordx4 v[138:139], v[92:95], off
	global_store_dwordx4 v[138:139], v[88:91], off offset:64
	global_store_dwordx4 v[138:139], v[84:87], off offset:512
	global_store_dwordx4 v[138:139], v[80:83], off offset:576
	s_nop 1
	v_add_u32_e32 v138, 0x30, v228
	v_ashrrev_i32_e32 v139, 31, v138
	v_lshlrev_b64 v[138:139], 12, v[138:139]
	v_lshl_add_u64 v[138:139], s[30:31], 0, v[138:139]
	v_lshl_add_u64 v[138:139], v[138:139], 0, v[232:233]
	global_store_dwordx4 v[138:139], v[76:79], off
	global_store_dwordx4 v[138:139], v[72:75], off offset:64
	global_store_dwordx4 v[138:139], v[68:71], off offset:512
	global_store_dwordx4 v[138:139], v[64:67], off offset:576
	s_nop 1
	v_add_u32_e32 v138, 0x80, v228
	v_ashrrev_i32_e32 v139, 31, v138
	v_lshlrev_b64 v[138:139], 12, v[138:139]
	v_lshl_add_u64 v[138:139], s[30:31], 0, v[138:139]
	v_lshl_add_u64 v[138:139], v[138:139], 0, v[232:233]
	global_store_dwordx4 v[138:139], v[60:63], off
	global_store_dwordx4 v[138:139], v[56:59], off offset:64
	global_store_dwordx4 v[138:139], v[52:55], off offset:512
	global_store_dwordx4 v[138:139], v[48:51], off offset:576
	s_nop 1
	v_add_u32_e32 v138, 0x90, v228
	v_ashrrev_i32_e32 v139, 31, v138
	v_lshlrev_b64 v[138:139], 12, v[138:139]
	v_lshl_add_u64 v[138:139], s[30:31], 0, v[138:139]
	v_lshl_add_u64 v[138:139], v[138:139], 0, v[232:233]
	global_store_dwordx4 v[138:139], v[44:47], off
	global_store_dwordx4 v[138:139], v[40:43], off offset:64
	global_store_dwordx4 v[138:139], v[36:39], off offset:512
	global_store_dwordx4 v[138:139], v[32:35], off offset:576
	s_nop 1
	v_add_u32_e32 v138, 0xa0, v228
	v_ashrrev_i32_e32 v139, 31, v138
	v_lshlrev_b64 v[138:139], 12, v[138:139]
	v_lshl_add_u64 v[138:139], s[30:31], 0, v[138:139]
	v_lshl_add_u64 v[138:139], v[138:139], 0, v[232:233]
	global_store_dwordx4 v[138:139], v[28:31], off
	global_store_dwordx4 v[138:139], v[24:27], off offset:64
	global_store_dwordx4 v[138:139], v[20:23], off offset:512
	global_store_dwordx4 v[138:139], v[16:19], off offset:576
	s_nop 1
	v_add_u32_e32 v138, 0xb0, v228
	v_ashrrev_i32_e32 v139, 31, v138
	v_lshlrev_b64 v[138:139], 12, v[138:139]
	v_lshl_add_u64 v[138:139], s[30:31], 0, v[138:139]
	v_lshl_add_u64 v[138:139], v[138:139], 0, v[232:233]
	global_store_dwordx4 v[138:139], v[12:15], off
	global_store_dwordx4 v[138:139], v[8:11], off offset:64
	global_store_dwordx4 v[138:139], v[4:7], off offset:512
	global_store_dwordx4 v[138:139], v[0:3], off offset:576
	s_nop 1
.Lepi2_nost2_1:
	s_waitcnt lgkmcnt(0)
	ds_read2_b32 v[136:137], v249 offset1:16
	v_lshlrev_b64 v[138:139], 11, v[228:229]
	s_waitcnt lgkmcnt(0)
	v_pk_mul_f32 v[110:111], v[110:111], v[136:137] op_sel_hi:[1,0]
	v_pk_mul_f32 v[108:109], v[108:109], v[136:137] op_sel_hi:[1,0]
	v_cvt_pk_bf16_f32 v141, v110, v111
	v_cvt_pk_bf16_f32 v140, v108, v109
	v_lshl_add_u64 v[110:111], s[28:29], 0, v[138:139]
	v_lshlrev_b64 v[108:109], 1, v[224:225]
	v_pk_mul_f32 v[98:99], v[98:99], v[136:137] op_sel_hi:[1,0]
	v_pk_mul_f32 v[96:97], v[96:97], v[136:137] op_sel_hi:[1,0]
	v_lshl_add_u64 v[110:111], v[110:111], 0, v[108:109]
	v_pk_mul_f32 v[102:103], v[102:103], v[136:137] op_sel_hi:[1,0]
	v_pk_mul_f32 v[100:101], v[100:101], v[136:137] op_sel_hi:[1,0]
	v_cvt_pk_bf16_f32 v96, v96, v97
	v_cvt_pk_bf16_f32 v97, v98, v99
	v_cvt_pk_bf16_f32 v100, v100, v101
	v_cvt_pk_bf16_f32 v101, v102, v103
	global_store_dwordx2 v[110:111], v[96:97], off offset:288
	v_lshlrev_b64 v[96:97], 11, v[192:193]
	v_mov_b32_e32 v98, v137
	global_store_dwordx2 v[110:111], v[100:101], off offset:256
	v_pk_mul_f32 v[100:101], v[126:127], v[98:99] op_sel_hi:[1,0]
	v_pk_mul_f32 v[102:103], v[124:125], v[98:99] op_sel_hi:[1,0]
	v_lshl_add_u64 v[96:97], s[28:29], 0, v[96:97]
	v_cvt_pk_bf16_f32 v102, v102, v103
	v_cvt_pk_bf16_f32 v103, v100, v101
	v_lshl_add_u64 v[96:97], v[96:97], 0, v[108:109]
	global_store_dwordx2 v[96:97], v[102:103], off
	v_pk_mul_f32 v[100:101], v[122:123], v[98:99] op_sel_hi:[1,0]
	v_pk_mul_f32 v[102:103], v[120:121], v[98:99] op_sel_hi:[1,0]
	v_pk_mul_f32 v[106:107], v[106:107], v[136:137] op_sel_hi:[1,0]
	v_cvt_pk_bf16_f32 v102, v102, v103
	v_cvt_pk_bf16_f32 v103, v100, v101
	global_store_dwordx2 v[96:97], v[102:103], off offset:32
	v_pk_mul_f32 v[100:101], v[118:119], v[98:99] op_sel_hi:[1,0]
	v_pk_mul_f32 v[102:103], v[116:117], v[98:99] op_sel_hi:[1,0]
	v_pk_mul_f32 v[104:105], v[104:105], v[136:137] op_sel_hi:[1,0]
	v_cvt_pk_bf16_f32 v102, v102, v103
	v_cvt_pk_bf16_f32 v103, v100, v101
	global_store_dwordx2 v[96:97], v[102:103], off offset:256
	ds_read2_b32 v[102:103], v249 offset0:32 offset1:48
	v_pk_mul_f32 v[100:101], v[114:115], v[98:99] op_sel_hi:[1,0]
	v_pk_mul_f32 v[98:99], v[112:113], v[98:99] op_sel_hi:[1,0]
	v_cvt_pk_bf16_f32 v104, v104, v105
	v_cvt_pk_bf16_f32 v98, v98, v99
	v_cvt_pk_bf16_f32 v99, v100, v101
	global_store_dwordx2 v[96:97], v[98:99], off offset:288
	v_lshlrev_b64 v[96:97], 11, v[176:177]
	s_waitcnt lgkmcnt(0)
	v_pk_mul_f32 v[94:95], v[94:95], v[102:103] op_sel_hi:[1,0]
	v_pk_mul_f32 v[92:93], v[92:93], v[102:103] op_sel_hi:[1,0]
	v_pk_mul_f32 v[82:83], v[82:83], v[102:103] op_sel_hi:[1,0]
	v_cvt_pk_bf16_f32 v92, v92, v93
	v_cvt_pk_bf16_f32 v93, v94, v95
	v_lshl_add_u64 v[94:95], s[28:29], 0, v[96:97]
	v_pk_mul_f32 v[80:81], v[80:81], v[102:103] op_sel_hi:[1,0]
	v_lshl_add_u64 v[94:95], v[94:95], 0, v[108:109]
	v_cvt_pk_bf16_f32 v80, v80, v81
	v_cvt_pk_bf16_f32 v81, v82, v83
	v_mov_b32_e32 v82, v103
	global_store_dwordx2 v[94:95], v[80:81], off offset:288
	v_lshlrev_b64 v[80:81], 11, v[160:161]
	v_pk_mul_f32 v[78:79], v[78:79], v[82:83] op_sel_hi:[1,0]
	v_pk_mul_f32 v[76:77], v[76:77], v[82:83] op_sel_hi:[1,0]
	v_pk_mul_f32 v[70:71], v[70:71], v[82:83] op_sel_hi:[1,0]
	v_cvt_pk_bf16_f32 v76, v76, v77
	v_cvt_pk_bf16_f32 v77, v78, v79
	v_lshl_add_u64 v[78:79], s[28:29], 0, v[80:81]
	v_pk_mul_f32 v[68:69], v[68:69], v[82:83] op_sel_hi:[1,0]
	v_lshl_add_u64 v[78:79], v[78:79], 0, v[108:109]
	v_cvt_pk_bf16_f32 v68, v68, v69
	v_cvt_pk_bf16_f32 v69, v70, v71
	global_store_dwordx2 v[78:79], v[68:69], off offset:256
	ds_read2_b32 v[68:69], v249 offset0:128 offset1:144
	v_pk_mul_f32 v[66:67], v[66:67], v[82:83] op_sel_hi:[1,0]
	v_pk_mul_f32 v[64:65], v[64:65], v[82:83] op_sel_hi:[1,0]
	v_pk_mul_f32 v[90:91], v[90:91], v[102:103] op_sel_hi:[1,0]
	v_cvt_pk_bf16_f32 v64, v64, v65
	v_cvt_pk_bf16_f32 v65, v66, v67
	global_store_dwordx2 v[78:79], v[64:65], off offset:288
	v_lshlrev_b64 v[64:65], 11, v[128:129]
	s_waitcnt lgkmcnt(0)
	v_pk_mul_f32 v[62:63], v[62:63], v[68:69] op_sel_hi:[1,0]
	v_pk_mul_f32 v[60:61], v[60:61], v[68:69] op_sel_hi:[1,0]
	v_pk_mul_f32 v[50:51], v[50:51], v[68:69] op_sel_hi:[1,0]
	v_cvt_pk_bf16_f32 v60, v60, v61
	v_cvt_pk_bf16_f32 v61, v62, v63
	v_lshl_add_u64 v[62:63], s[28:29], 0, v[64:65]
	v_pk_mul_f32 v[48:49], v[48:49], v[68:69] op_sel_hi:[1,0]
	v_lshl_add_u64 v[62:63], v[62:63], 0, v[108:109]
	v_cvt_pk_bf16_f32 v48, v48, v49
	v_cvt_pk_bf16_f32 v49, v50, v51
	v_mov_b32_e32 v50, v69
	global_store_dwordx2 v[62:63], v[48:49], off offset:288
	v_lshlrev_b64 v[48:49], 11, v[130:131]
	v_pk_mul_f32 v[46:47], v[46:47], v[50:51] op_sel_hi:[1,0]
	v_pk_mul_f32 v[44:45], v[44:45], v[50:51] op_sel_hi:[1,0]
	v_pk_mul_f32 v[38:39], v[38:39], v[50:51] op_sel_hi:[1,0]
	v_cvt_pk_bf16_f32 v44, v44, v45
	v_cvt_pk_bf16_f32 v45, v46, v47
	v_lshl_add_u64 v[46:47], s[28:29], 0, v[48:49]
	v_pk_mul_f32 v[36:37], v[36:37], v[50:51] op_sel_hi:[1,0]
	v_lshl_add_u64 v[46:47], v[46:47], 0, v[108:109]
	v_cvt_pk_bf16_f32 v36, v36, v37
	v_cvt_pk_bf16_f32 v37, v38, v39
	global_store_dwordx2 v[46:47], v[36:37], off offset:256
	ds_read2_b32 v[36:37], v249 offset0:160 offset1:176
	v_pk_mul_f32 v[34:35], v[34:35], v[50:51] op_sel_hi:[1,0]
	v_pk_mul_f32 v[32:33], v[32:33], v[50:51] op_sel_hi:[1,0]
	v_pk_mul_f32 v[88:89], v[88:89], v[102:103] op_sel_hi:[1,0]
	v_cvt_pk_bf16_f32 v32, v32, v33
	v_cvt_pk_bf16_f32 v33, v34, v35
	global_store_dwordx2 v[46:47], v[32:33], off offset:288
	v_lshlrev_b64 v[32:33], 11, v[132:133]
	s_waitcnt lgkmcnt(0)
	v_pk_mul_f32 v[30:31], v[30:31], v[36:37] op_sel_hi:[1,0]
	v_pk_mul_f32 v[28:29], v[28:29], v[36:37] op_sel_hi:[1,0]
	v_pk_mul_f32 v[18:19], v[18:19], v[36:37] op_sel_hi:[1,0]
	v_cvt_pk_bf16_f32 v28, v28, v29
	v_cvt_pk_bf16_f32 v29, v30, v31
	v_lshl_add_u64 v[30:31], s[28:29], 0, v[32:33]
	v_pk_mul_f32 v[16:17], v[16:17], v[36:37] op_sel_hi:[1,0]
	v_lshl_add_u64 v[30:31], v[30:31], 0, v[108:109]
	v_cvt_pk_bf16_f32 v16, v16, v17
	v_cvt_pk_bf16_f32 v17, v18, v19
	v_mov_b32_e32 v18, v37
	global_store_dwordx2 v[30:31], v[16:17], off offset:288
	v_lshlrev_b64 v[16:17], 11, v[134:135]
	v_pk_mul_f32 v[14:15], v[14:15], v[18:19] op_sel_hi:[1,0]
	v_pk_mul_f32 v[12:13], v[12:13], v[18:19] op_sel_hi:[1,0]
	v_pk_mul_f32 v[86:87], v[86:87], v[102:103] op_sel_hi:[1,0]
	v_pk_mul_f32 v[84:85], v[84:85], v[102:103] op_sel_hi:[1,0]
	v_pk_mul_f32 v[74:75], v[74:75], v[82:83] op_sel_hi:[1,0]
	v_pk_mul_f32 v[72:73], v[72:73], v[82:83] op_sel_hi:[1,0]
	v_pk_mul_f32 v[58:59], v[58:59], v[68:69] op_sel_hi:[1,0]
	v_pk_mul_f32 v[56:57], v[56:57], v[68:69] op_sel_hi:[1,0]
	v_pk_mul_f32 v[54:55], v[54:55], v[68:69] op_sel_hi:[1,0]
	v_pk_mul_f32 v[52:53], v[52:53], v[68:69] op_sel_hi:[1,0]
	v_pk_mul_f32 v[42:43], v[42:43], v[50:51] op_sel_hi:[1,0]
	v_pk_mul_f32 v[40:41], v[40:41], v[50:51] op_sel_hi:[1,0]
	v_pk_mul_f32 v[26:27], v[26:27], v[36:37] op_sel_hi:[1,0]
	v_pk_mul_f32 v[24:25], v[24:25], v[36:37] op_sel_hi:[1,0]
	v_pk_mul_f32 v[22:23], v[22:23], v[36:37] op_sel_hi:[1,0]
	v_pk_mul_f32 v[20:21], v[20:21], v[36:37] op_sel_hi:[1,0]
	v_cvt_pk_bf16_f32 v12, v12, v13
	v_cvt_pk_bf16_f32 v13, v14, v15
	v_lshl_add_u64 v[14:15], s[28:29], 0, v[16:17]
	v_pk_mul_f32 v[10:11], v[10:11], v[18:19] op_sel_hi:[1,0]
	v_pk_mul_f32 v[8:9], v[8:9], v[18:19] op_sel_hi:[1,0]
	v_pk_mul_f32 v[6:7], v[6:7], v[18:19] op_sel_hi:[1,0]
	v_pk_mul_f32 v[4:5], v[4:5], v[18:19] op_sel_hi:[1,0]
	v_pk_mul_f32 v[2:3], v[2:3], v[18:19] op_sel_hi:[1,0]
	v_pk_mul_f32 v[0:1], v[0:1], v[18:19] op_sel_hi:[1,0]
	v_cvt_pk_bf16_f32 v105, v106, v107
	v_cvt_pk_bf16_f32 v88, v88, v89
	v_cvt_pk_bf16_f32 v89, v90, v91
	v_cvt_pk_bf16_f32 v84, v84, v85
	v_cvt_pk_bf16_f32 v85, v86, v87
	v_cvt_pk_bf16_f32 v72, v72, v73
	v_cvt_pk_bf16_f32 v73, v74, v75
	v_cvt_pk_bf16_f32 v56, v56, v57
	v_cvt_pk_bf16_f32 v57, v58, v59
	v_cvt_pk_bf16_f32 v52, v52, v53
	v_cvt_pk_bf16_f32 v53, v54, v55
	v_cvt_pk_bf16_f32 v40, v40, v41
	v_cvt_pk_bf16_f32 v41, v42, v43
	v_cvt_pk_bf16_f32 v24, v24, v25
	v_cvt_pk_bf16_f32 v25, v26, v27
	v_cvt_pk_bf16_f32 v20, v20, v21
	v_cvt_pk_bf16_f32 v21, v22, v23
	v_lshl_add_u64 v[14:15], v[14:15], 0, v[108:109]
	v_cvt_pk_bf16_f32 v8, v8, v9
	v_cvt_pk_bf16_f32 v9, v10, v11
	v_cvt_pk_bf16_f32 v4, v4, v5
	v_cvt_pk_bf16_f32 v5, v6, v7
	v_cvt_pk_bf16_f32 v0, v0, v1
	v_cvt_pk_bf16_f32 v1, v2, v3
	global_store_dwordx2 v[110:111], v[140:141], off
	global_store_dwordx2 v[110:111], v[104:105], off offset:32
	global_store_dwordx2 v[94:95], v[92:93], off
	global_store_dwordx2 v[94:95], v[88:89], off offset:32
	global_store_dwordx2 v[94:95], v[84:85], off offset:256
	global_store_dwordx2 v[78:79], v[76:77], off
	global_store_dwordx2 v[78:79], v[72:73], off offset:32
	global_store_dwordx2 v[62:63], v[60:61], off
	global_store_dwordx2 v[62:63], v[56:57], off offset:32
	global_store_dwordx2 v[62:63], v[52:53], off offset:256
	global_store_dwordx2 v[46:47], v[44:45], off
	global_store_dwordx2 v[46:47], v[40:41], off offset:32
	global_store_dwordx2 v[30:31], v[28:29], off
	global_store_dwordx2 v[30:31], v[24:25], off offset:32
	global_store_dwordx2 v[30:31], v[20:21], off offset:256
	global_store_dwordx2 v[14:15], v[12:13], off
	global_store_dwordx2 v[14:15], v[8:9], off offset:32
	global_store_dwordx2 v[14:15], v[4:5], off offset:256
	global_store_dwordx2 v[14:15], v[0:1], off offset:288

.LBB0_168:
	s_or_b64 exec, exec, s[4:5]
	v_lshlrev_b64 v[232:233], 2, v[224:225]
	s_waitcnt lgkmcnt(0)
	s_barrier
	s_waitcnt lgkmcnt(0)
	v_lshl_add_u64 v[144:145], s[60:61], 0, v[232:233]
	global_load_dwordx4 v[156:159], v[144:145], off
	global_load_dwordx4 v[152:155], v[144:145], off offset:64
	global_load_dwordx4 v[148:151], v[144:145], off offset:512
	s_nop 0
	global_load_dwordx4 v[144:147], v[144:145], off offset:576
	v_lshl_add_u32 v210, v228, 2, 0
	v_add_u32_e32 v247, 0x1000, v210
	ds_read2_b32 v[210:211], v247 offset1:16
	v_add_u32_e32 v228, s17, v228
	v_ashrrev_i32_e32 v229, 31, v228
	v_readlane_b32 s4, v255, 11
	v_readlane_b32 s5, v255, 12
	s_waitcnt lgkmcnt(0)
	v_pk_mul_f32 v[96:97], v[96:97], v[210:211] op_sel_hi:[1,0]
	v_pk_mul_f32 v[98:99], v[98:99], v[210:211] op_sel_hi:[1,0]
	v_pk_mul_f32 v[108:109], v[108:109], v[210:211] op_sel_hi:[1,0]
	v_pk_mul_f32 v[110:111], v[110:111], v[210:211] op_sel_hi:[1,0]
	v_pk_mul_f32 v[104:105], v[104:105], v[210:211] op_sel_hi:[1,0]
	v_pk_mul_f32 v[106:107], v[106:107], v[210:211] op_sel_hi:[1,0]
	v_pk_mul_f32 v[100:101], v[100:101], v[210:211] op_sel_hi:[1,0]
	v_pk_mul_f32 v[102:103], v[102:103], v[210:211] op_sel_hi:[1,0]
	s_andn2_b64 vcc, exec, s[4:5]
	s_waitcnt vmcnt(0)
	v_pk_fma_f32 v[108:109], v[156:157], v[108:109], v[204:205]
	v_lshlrev_b64 v[204:205], 12, v[228:229]
	v_lshl_add_u64 v[204:205], s[30:31], 0, v[204:205]
	v_pk_fma_f32 v[98:99], v[146:147], v[98:99], v[194:195]
	v_pk_fma_f32 v[96:97], v[144:145], v[96:97], v[192:193]
	v_add_u32_e32 v192, 16, v228
	v_mov_b32_e32 v194, v211
	v_ashrrev_i32_e32 v193, 31, v192
	v_pk_mul_f32 v[124:125], v[124:125], v[194:195] op_sel_hi:[1,0]
	v_pk_mul_f32 v[126:127], v[126:127], v[194:195] op_sel_hi:[1,0]
	v_pk_fma_f32 v[124:125], v[156:157], v[124:125], v[188:189]
	v_lshlrev_b64 v[188:189], 12, v[192:193]
	v_lshl_add_u64 v[188:189], s[30:31], 0, v[188:189]
	v_pk_mul_f32 v[120:121], v[120:121], v[194:195] op_sel_hi:[1,0]
	v_pk_mul_f32 v[122:123], v[122:123], v[194:195] op_sel_hi:[1,0]
	v_pk_mul_f32 v[116:117], v[116:117], v[194:195] op_sel_hi:[1,0]
	v_pk_mul_f32 v[118:119], v[118:119], v[194:195] op_sel_hi:[1,0]
	v_pk_mul_f32 v[112:113], v[112:113], v[194:195] op_sel_hi:[1,0]
	v_pk_mul_f32 v[114:115], v[114:115], v[194:195] op_sel_hi:[1,0]
	v_pk_fma_f32 v[110:111], v[158:159], v[110:111], v[206:207]
	v_lshl_add_u64 v[204:205], v[204:205], 0, v[232:233]
	v_pk_fma_f32 v[106:107], v[154:155], v[106:107], v[202:203]
	v_pk_fma_f32 v[104:105], v[152:153], v[104:105], v[200:201]
	v_pk_fma_f32 v[102:103], v[150:151], v[102:103], v[198:199]
	v_pk_fma_f32 v[100:101], v[148:149], v[100:101], v[196:197]
	v_pk_fma_f32 v[126:127], v[158:159], v[126:127], v[190:191]
	v_lshl_add_u64 v[188:189], v[188:189], 0, v[232:233]
	v_pk_fma_f32 v[122:123], v[154:155], v[122:123], v[186:187]
	v_pk_fma_f32 v[120:121], v[152:153], v[120:121], v[184:185]
	v_pk_fma_f32 v[118:119], v[150:151], v[118:119], v[182:183]
	v_pk_fma_f32 v[116:117], v[148:149], v[116:117], v[180:181]
	v_pk_fma_f32 v[114:115], v[146:147], v[114:115], v[178:179]
	v_pk_fma_f32 v[112:113], v[144:145], v[112:113], v[176:177]
	ds_read2_b32 v[178:179], v247 offset0:32 offset1:48
	v_add_u32_e32 v176, 32, v228
	v_ashrrev_i32_e32 v177, 31, v176
	s_waitcnt lgkmcnt(0)
	v_pk_mul_f32 v[80:81], v[80:81], v[178:179] op_sel_hi:[1,0]
	v_pk_mul_f32 v[82:83], v[82:83], v[178:179] op_sel_hi:[1,0]
	v_pk_fma_f32 v[80:81], v[144:145], v[80:81], v[160:161]
	v_pk_fma_f32 v[82:83], v[146:147], v[82:83], v[162:163]
	v_add_u32_e32 v160, 48, v228
	v_mov_b32_e32 v162, v179
	v_pk_mul_f32 v[92:93], v[92:93], v[178:179] op_sel_hi:[1,0]
	v_ashrrev_i32_e32 v161, 31, v160
	v_pk_mul_f32 v[76:77], v[76:77], v[162:163] op_sel_hi:[1,0]
	v_pk_mul_f32 v[64:65], v[64:65], v[162:163] op_sel_hi:[1,0]
	v_pk_fma_f32 v[92:93], v[156:157], v[92:93], v[172:173]
	v_lshlrev_b64 v[172:173], 12, v[176:177]
	v_pk_fma_f32 v[76:77], v[156:157], v[76:77], v[140:141]
	v_lshlrev_b64 v[140:141], 12, v[160:161]
	v_pk_fma_f32 v[64:65], v[144:145], v[64:65], v[128:129]
	v_add_u32_e32 v128, 0x80, v228
	v_pk_mul_f32 v[94:95], v[94:95], v[178:179] op_sel_hi:[1,0]
	v_lshl_add_u64 v[172:173], s[30:31], 0, v[172:173]
	v_pk_mul_f32 v[88:89], v[88:89], v[178:179] op_sel_hi:[1,0]
	v_pk_mul_f32 v[90:91], v[90:91], v[178:179] op_sel_hi:[1,0]
	v_pk_mul_f32 v[84:85], v[84:85], v[178:179] op_sel_hi:[1,0]
	v_pk_mul_f32 v[86:87], v[86:87], v[178:179] op_sel_hi:[1,0]
	v_pk_mul_f32 v[78:79], v[78:79], v[162:163] op_sel_hi:[1,0]
	v_lshl_add_u64 v[140:141], s[30:31], 0, v[140:141]
	v_pk_mul_f32 v[72:73], v[72:73], v[162:163] op_sel_hi:[1,0]
	v_pk_mul_f32 v[74:75], v[74:75], v[162:163] op_sel_hi:[1,0]
	v_pk_mul_f32 v[68:69], v[68:69], v[162:163] op_sel_hi:[1,0]
	v_pk_mul_f32 v[70:71], v[70:71], v[162:163] op_sel_hi:[1,0]
	v_pk_mul_f32 v[66:67], v[66:67], v[162:163] op_sel_hi:[1,0]
	v_ashrrev_i32_e32 v129, 31, v128
	v_pk_fma_f32 v[94:95], v[158:159], v[94:95], v[174:175]
	v_lshl_add_u64 v[172:173], v[172:173], 0, v[232:233]
	v_pk_fma_f32 v[90:91], v[154:155], v[90:91], v[170:171]
	v_pk_fma_f32 v[88:89], v[152:153], v[88:89], v[168:169]
	v_pk_fma_f32 v[86:87], v[150:151], v[86:87], v[166:167]
	v_pk_fma_f32 v[84:85], v[148:149], v[84:85], v[164:165]
	v_pk_fma_f32 v[78:79], v[158:159], v[78:79], v[142:143]
	v_lshl_add_u64 v[140:141], v[140:141], 0, v[232:233]
	v_pk_fma_f32 v[74:75], v[154:155], v[74:75], v[138:139]
	v_pk_fma_f32 v[72:73], v[152:153], v[72:73], v[136:137]
	v_pk_fma_f32 v[70:71], v[150:151], v[70:71], v[134:135]
	v_pk_fma_f32 v[68:69], v[148:149], v[68:69], v[132:133]
	v_pk_fma_f32 v[66:67], v[146:147], v[66:67], v[130:131]
	v_lshlrev_b64 v[130:131], 10, v[128:129]
	v_add_u32_e32 v130, 0x90, v228
	v_add_u32_e32 v132, 0xa0, v228
	v_add_u32_e32 v134, 0xb0, v228
	v_ashrrev_i32_e32 v131, 31, v130
	v_ashrrev_i32_e32 v133, 31, v132
	v_ashrrev_i32_e32 v135, 31, v134
	v_lshlrev_b64 v[162:163], 12, v[128:129]
	v_lshl_add_u64 v[162:163], v[230:231], 0, v[162:163]
	global_load_dwordx4 v[164:167], v[162:163], off
	global_load_dwordx4 v[168:171], v[162:163], off offset:64
	global_load_dwordx4 v[172:175], v[162:163], off offset:512
	global_load_dwordx4 v[180:183], v[162:163], off offset:576
	v_lshlrev_b64 v[162:163], 12, v[130:131]
	v_lshl_add_u64 v[162:163], v[230:231], 0, v[162:163]
	global_load_dwordx4 v[184:187], v[162:163], off
	global_load_dwordx4 v[188:191], v[162:163], off offset:64
	global_load_dwordx4 v[196:199], v[162:163], off offset:512
	global_load_dwordx4 v[200:203], v[162:163], off offset:576
	v_lshlrev_b64 v[162:163], 12, v[132:133]
	v_lshl_add_u64 v[162:163], v[230:231], 0, v[162:163]
	global_load_dwordx4 v[204:207], v[162:163], off
	global_load_dwordx4 v[136:139], v[162:163], off offset:64
	global_load_dwordx4 v[140:143], v[162:163], off offset:512
	global_load_dwordx4 v[210:213], v[162:163], off offset:576
	ds_read2_b32 v[194:195], v247 offset0:128 offset1:144
	ds_read2_b32 v[178:179], v247 offset0:160 offset1:176
	s_waitcnt lgkmcnt(0)
	v_pk_mul_f32 v[60:61], v[60:61], v[194:195] op_sel_hi:[1,0]
	v_pk_mul_f32 v[62:63], v[62:63], v[194:195] op_sel_hi:[1,0]
	v_pk_mul_f32 v[56:57], v[56:57], v[194:195] op_sel_hi:[1,0]
	v_pk_mul_f32 v[58:59], v[58:59], v[194:195] op_sel_hi:[1,0]
	v_pk_mul_f32 v[52:53], v[52:53], v[194:195] op_sel_hi:[1,0]
	v_pk_mul_f32 v[54:55], v[54:55], v[194:195] op_sel_hi:[1,0]
	v_pk_mul_f32 v[48:49], v[48:49], v[194:195] op_sel_hi:[1,0]
	v_pk_mul_f32 v[50:51], v[50:51], v[194:195] op_sel_hi:[1,0]
	v_mov_b32_e32 v194, v195
	v_pk_mul_f32 v[44:45], v[44:45], v[194:195] op_sel_hi:[1,0]
	v_pk_mul_f32 v[46:47], v[46:47], v[194:195] op_sel_hi:[1,0]
	v_pk_mul_f32 v[40:41], v[40:41], v[194:195] op_sel_hi:[1,0]
	v_pk_mul_f32 v[42:43], v[42:43], v[194:195] op_sel_hi:[1,0]
	v_pk_mul_f32 v[36:37], v[36:37], v[194:195] op_sel_hi:[1,0]
	v_pk_mul_f32 v[38:39], v[38:39], v[194:195] op_sel_hi:[1,0]
	v_pk_mul_f32 v[32:33], v[32:33], v[194:195] op_sel_hi:[1,0]
	v_pk_mul_f32 v[34:35], v[34:35], v[194:195] op_sel_hi:[1,0]
	v_pk_mul_f32 v[28:29], v[28:29], v[178:179] op_sel_hi:[1,0]
	v_pk_mul_f32 v[30:31], v[30:31], v[178:179] op_sel_hi:[1,0]
	v_pk_mul_f32 v[24:25], v[24:25], v[178:179] op_sel_hi:[1,0]
	v_pk_mul_f32 v[26:27], v[26:27], v[178:179] op_sel_hi:[1,0]
	v_pk_mul_f32 v[20:21], v[20:21], v[178:179] op_sel_hi:[1,0]
	v_pk_mul_f32 v[22:23], v[22:23], v[178:179] op_sel_hi:[1,0]
	v_pk_mul_f32 v[16:17], v[16:17], v[178:179] op_sel_hi:[1,0]
	v_pk_mul_f32 v[18:19], v[18:19], v[178:179] op_sel_hi:[1,0]
	v_mov_b32_e32 v178, v179
	v_pk_mul_f32 v[12:13], v[12:13], v[178:179] op_sel_hi:[1,0]
	v_pk_mul_f32 v[14:15], v[14:15], v[178:179] op_sel_hi:[1,0]
	v_pk_mul_f32 v[8:9], v[8:9], v[178:179] op_sel_hi:[1,0]
	v_pk_mul_f32 v[10:11], v[10:11], v[178:179] op_sel_hi:[1,0]
	v_pk_mul_f32 v[4:5], v[4:5], v[178:179] op_sel_hi:[1,0]
	v_pk_mul_f32 v[6:7], v[6:7], v[178:179] op_sel_hi:[1,0]
	v_pk_mul_f32 v[0:1], v[0:1], v[178:179] op_sel_hi:[1,0]
	v_pk_mul_f32 v[2:3], v[2:3], v[178:179] op_sel_hi:[1,0]
	s_waitcnt vmcnt(11)
	v_pk_fma_f32 v[60:61], v[156:157], v[60:61], v[164:165]
	v_pk_fma_f32 v[62:63], v[158:159], v[62:63], v[166:167]
	s_waitcnt vmcnt(10)
	v_pk_fma_f32 v[56:57], v[152:153], v[56:57], v[168:169]
	v_pk_fma_f32 v[58:59], v[154:155], v[58:59], v[170:171]
	s_waitcnt vmcnt(9)
	v_pk_fma_f32 v[52:53], v[148:149], v[52:53], v[172:173]
	v_pk_fma_f32 v[54:55], v[150:151], v[54:55], v[174:175]
	s_waitcnt vmcnt(8)
	v_pk_fma_f32 v[48:49], v[144:145], v[48:49], v[180:181]
	v_pk_fma_f32 v[50:51], v[146:147], v[50:51], v[182:183]
	v_lshlrev_b64 v[162:163], 12, v[134:135]
	v_lshl_add_u64 v[162:163], v[230:231], 0, v[162:163]
	global_load_dwordx4 v[164:167], v[162:163], off
	global_load_dwordx4 v[168:171], v[162:163], off offset:64
	global_load_dwordx4 v[172:175], v[162:163], off offset:512
	global_load_dwordx4 v[180:183], v[162:163], off offset:576
	s_waitcnt vmcnt(11)
	v_pk_fma_f32 v[44:45], v[156:157], v[44:45], v[184:185]
	v_pk_fma_f32 v[46:47], v[158:159], v[46:47], v[186:187]
	s_waitcnt vmcnt(10)
	v_pk_fma_f32 v[40:41], v[152:153], v[40:41], v[188:189]
	v_pk_fma_f32 v[42:43], v[154:155], v[42:43], v[190:191]
	s_waitcnt vmcnt(9)
	v_pk_fma_f32 v[36:37], v[148:149], v[36:37], v[196:197]
	v_pk_fma_f32 v[38:39], v[150:151], v[38:39], v[198:199]
	s_waitcnt vmcnt(8)
	v_pk_fma_f32 v[32:33], v[144:145], v[32:33], v[200:201]
	v_pk_fma_f32 v[34:35], v[146:147], v[34:35], v[202:203]
	s_waitcnt vmcnt(7)
	v_pk_fma_f32 v[28:29], v[156:157], v[28:29], v[204:205]
	v_pk_fma_f32 v[30:31], v[158:159], v[30:31], v[206:207]
	s_waitcnt vmcnt(6)
	v_pk_fma_f32 v[24:25], v[152:153], v[24:25], v[136:137]
	v_pk_fma_f32 v[26:27], v[154:155], v[26:27], v[138:139]
	s_waitcnt vmcnt(5)
	v_pk_fma_f32 v[20:21], v[148:149], v[20:21], v[140:141]
	v_pk_fma_f32 v[22:23], v[150:151], v[22:23], v[142:143]
	s_waitcnt vmcnt(4)
	v_pk_fma_f32 v[16:17], v[144:145], v[16:17], v[210:211]
	v_pk_fma_f32 v[18:19], v[146:147], v[18:19], v[212:213]
	s_waitcnt vmcnt(3)
	v_pk_fma_f32 v[12:13], v[156:157], v[12:13], v[164:165]
	v_pk_fma_f32 v[14:15], v[158:159], v[14:15], v[166:167]
	s_waitcnt vmcnt(2)
	v_pk_fma_f32 v[8:9], v[152:153], v[8:9], v[168:169]
	v_pk_fma_f32 v[10:11], v[154:155], v[10:11], v[170:171]
	s_waitcnt vmcnt(1)
	v_pk_fma_f32 v[4:5], v[148:149], v[4:5], v[172:173]
	v_pk_fma_f32 v[6:7], v[150:151], v[6:7], v[174:175]
	s_waitcnt vmcnt(0)
	v_pk_fma_f32 v[0:1], v[144:145], v[0:1], v[180:181]
	v_pk_fma_f32 v[2:3], v[146:147], v[2:3], v[182:183]
	s_cbranch_vccz .Lepi2_st2_2
	v_mov_b32_e32 v138, v228
	v_ashrrev_i32_e32 v139, 31, v138
	v_lshlrev_b64 v[138:139], 12, v[138:139]
	v_lshl_add_u64 v[138:139], s[30:31], 0, v[138:139]
	v_lshl_add_u64 v[138:139], v[138:139], 0, v[232:233]
	global_store_dwordx4 v[138:139], v[108:111], off
	global_store_dwordx4 v[138:139], v[104:107], off offset:64
	global_store_dwordx4 v[138:139], v[100:103], off offset:512
	global_store_dwordx4 v[138:139], v[96:99], off offset:576
	s_nop 1
	v_add_u32_e32 v138, 0x10, v228
	v_ashrrev_i32_e32 v139, 31, v138
	v_lshlrev_b64 v[138:139], 12, v[138:139]
	v_lshl_add_u64 v[138:139], s[30:31], 0, v[138:139]
	v_lshl_add_u64 v[138:139], v[138:139], 0, v[232:233]
	global_store_dwordx4 v[138:139], v[124:127], off
	global_store_dwordx4 v[138:139], v[120:123], off offset:64
	global_store_dwordx4 v[138:139], v[116:119], off offset:512
	global_store_dwordx4 v[138:139], v[112:115], off offset:576
	s_nop 1
	v_add_u32_e32 v138, 0x20, v228
	v_ashrrev_i32_e32 v139, 31, v138
	v_lshlrev_b64 v[138:139], 12, v[138:139]
	v_lshl_add_u64 v[138:139], s[30:31], 0, v[138:139]
	v_lshl_add_u64 v[138:139], v[138:139], 0, v[232:233]
	global_store_dwordx4 v[138:139], v[92:95], off
	global_store_dwordx4 v[138:139], v[88:91], off offset:64
	global_store_dwordx4 v[138:139], v[84:87], off offset:512
	global_store_dwordx4 v[138:139], v[80:83], off offset:576
	s_nop 1
	v_add_u32_e32 v138, 0x30, v228
	v_ashrrev_i32_e32 v139, 31, v138
	v_lshlrev_b64 v[138:139], 12, v[138:139]
	v_lshl_add_u64 v[138:139], s[30:31], 0, v[138:139]
	v_lshl_add_u64 v[138:139], v[138:139], 0, v[232:233]
	global_store_dwordx4 v[138:139], v[76:79], off
	global_store_dwordx4 v[138:139], v[72:75], off offset:64
	global_store_dwordx4 v[138:139], v[68:71], off offset:512
	global_store_dwordx4 v[138:139], v[64:67], off offset:576
	s_nop 1
	v_add_u32_e32 v138, 0x80, v228
	v_ashrrev_i32_e32 v139, 31, v138
	v_lshlrev_b64 v[138:139], 12, v[138:139]
	v_lshl_add_u64 v[138:139], s[30:31], 0, v[138:139]
	v_lshl_add_u64 v[138:139], v[138:139], 0, v[232:233]
	global_store_dwordx4 v[138:139], v[60:63], off
	global_store_dwordx4 v[138:139], v[56:59], off offset:64
	global_store_dwordx4 v[138:139], v[52:55], off offset:512
	global_store_dwordx4 v[138:139], v[48:51], off offset:576
	s_nop 1
	v_add_u32_e32 v138, 0x90, v228
	v_ashrrev_i32_e32 v139, 31, v138
	v_lshlrev_b64 v[138:139], 12, v[138:139]
	v_lshl_add_u64 v[138:139], s[30:31], 0, v[138:139]
	v_lshl_add_u64 v[138:139], v[138:139], 0, v[232:233]
	global_store_dwordx4 v[138:139], v[44:47], off
	global_store_dwordx4 v[138:139], v[40:43], off offset:64
	global_store_dwordx4 v[138:139], v[36:39], off offset:512
	global_store_dwordx4 v[138:139], v[32:35], off offset:576
	s_nop 1
	v_add_u32_e32 v138, 0xa0, v228
	v_ashrrev_i32_e32 v139, 31, v138
	v_lshlrev_b64 v[138:139], 12, v[138:139]
	v_lshl_add_u64 v[138:139], s[30:31], 0, v[138:139]
	v_lshl_add_u64 v[138:139], v[138:139], 0, v[232:233]
	global_store_dwordx4 v[138:139], v[28:31], off
	global_store_dwordx4 v[138:139], v[24:27], off offset:64
	global_store_dwordx4 v[138:139], v[20:23], off offset:512
	global_store_dwordx4 v[138:139], v[16:19], off offset:576
	s_nop 1
	v_add_u32_e32 v138, 0xb0, v228
	v_ashrrev_i32_e32 v139, 31, v138
	v_lshlrev_b64 v[138:139], 12, v[138:139]
	v_lshl_add_u64 v[138:139], s[30:31], 0, v[138:139]
	v_lshl_add_u64 v[138:139], v[138:139], 0, v[232:233]
	global_store_dwordx4 v[138:139], v[12:15], off
	global_store_dwordx4 v[138:139], v[8:11], off offset:64
	global_store_dwordx4 v[138:139], v[4:7], off offset:512
	global_store_dwordx4 v[138:139], v[0:3], off offset:576
	s_nop 1
	s_branch .LBB0_203
.Lepi2_st2_2:
	v_mul_f32_e32 v136, v109, v109
	v_mul_f32_e32 v137, v111, v111
	v_fmac_f32_e32 v136, v108, v108
	v_fmac_f32_e32 v137, v110, v110
	v_add_f32_e32 v136, v136, v137
	v_mul_f32_e32 v137, v105, v105
	v_mul_f32_e32 v138, v107, v107
	v_fmac_f32_e32 v137, v104, v104
	v_fmac_f32_e32 v138, v106, v106
	v_add_f32_e32 v137, v137, v138
	v_add_f32_e32 v136, v136, v137
	v_mul_f32_e32 v137, v101, v101
	v_mul_f32_e32 v138, v103, v103
	v_fmac_f32_e32 v137, v100, v100
	v_fmac_f32_e32 v138, v102, v102
	v_add_f32_e32 v137, v137, v138
	v_add_f32_e32 v136, v137, v136
	v_mul_f32_e32 v137, v97, v97
	v_mul_f32_e32 v138, v99, v99
	v_fmac_f32_e32 v137, v96, v96
	v_fmac_f32_e32 v138, v98, v98
	v_add_f32_e32 v137, v137, v138
	v_add_f32_e32 v136, v137, v136
	ds_bpermute_b32 v137, v208, v136
	s_waitcnt lgkmcnt(0)
	v_add_f32_e32 v136, v136, v137
	ds_bpermute_b32 v137, v223, v136
	s_and_saveexec_b64 s[4:5], s[8:9]
	s_cbranch_execz .LBB0_171
	s_lshl_b32 s14, s66, 10
	s_add_i32 s14, s36, s14
	v_lshl_add_u32 v138, v221, 4, s14
	s_waitcnt lgkmcnt(0)
	v_add_f32_e32 v136, v136, v137
	ds_write_b32 v138, v136

.LBB0_200:
	s_waitcnt lgkmcnt(0)
	s_barrier
	s_and_saveexec_b64 s[4:5], s[10:11]
	s_cbranch_execz .LBB0_202
	s_waitcnt lgkmcnt(0)
	v_lshl_add_u64 v[136:137], v[226:227], 4, s[40:41]
	global_load_dword v138, v[136:137], off sc1
	global_load_dword v139, v[136:137], off offset:4 sc1
	global_load_dword v140, v[136:137], off offset:8 sc1
	global_load_dword v141, v[136:137], off offset:12 sc1
	s_waitcnt vmcnt(0)
	v_add_f32_e32 v138, 0, v138
	v_add_f32_e32 v138, v138, v139
	v_add_f32_e32 v138, v138, v140
	v_add_f32_e32 v136, v138, v141
	v_fmamk_f32 v136, v136, 0x3a800000, v236
	v_cmp_gt_f32_e32 vcc, s3, v136
	v_mul_f32_e32 v137, 0x4b800000, v136
	s_nop 0
	v_cndmask_b32_e32 v136, v136, v137, vcc
	v_rsq_f32_e32 v136, v136
	s_nop 0
	v_mul_f32_e32 v137, 0x45800000, v136
	v_cndmask_b32_e32 v136, v136, v137, vcc
	v_lshl_add_u32 v137, v248, 2, 0
	ds_write_b32 v137, v136 offset:4096

.Lepi2_nost2_2:
	s_waitcnt lgkmcnt(0)
	ds_read2_b32 v[136:137], v247 offset1:16
	v_lshlrev_b64 v[138:139], 11, v[228:229]
	s_waitcnt lgkmcnt(0)
	v_pk_mul_f32 v[110:111], v[110:111], v[136:137] op_sel_hi:[1,0]
	v_pk_mul_f32 v[108:109], v[108:109], v[136:137] op_sel_hi:[1,0]
	v_cvt_pk_bf16_f32 v141, v110, v111
	v_cvt_pk_bf16_f32 v140, v108, v109
	v_lshl_add_u64 v[110:111], s[28:29], 0, v[138:139]
	v_lshlrev_b64 v[108:109], 1, v[224:225]
	v_pk_mul_f32 v[98:99], v[98:99], v[136:137] op_sel_hi:[1,0]
	v_pk_mul_f32 v[96:97], v[96:97], v[136:137] op_sel_hi:[1,0]
	v_lshl_add_u64 v[110:111], v[110:111], 0, v[108:109]
	v_pk_mul_f32 v[102:103], v[102:103], v[136:137] op_sel_hi:[1,0]
	v_pk_mul_f32 v[100:101], v[100:101], v[136:137] op_sel_hi:[1,0]
	v_cvt_pk_bf16_f32 v96, v96, v97
	v_cvt_pk_bf16_f32 v97, v98, v99
	v_cvt_pk_bf16_f32 v100, v100, v101
	v_cvt_pk_bf16_f32 v101, v102, v103
	global_store_dwordx2 v[110:111], v[96:97], off offset:288
	v_lshlrev_b64 v[96:97], 11, v[192:193]
	v_mov_b32_e32 v98, v137
	global_store_dwordx2 v[110:111], v[100:101], off offset:256
	v_pk_mul_f32 v[100:101], v[126:127], v[98:99] op_sel_hi:[1,0]
	v_pk_mul_f32 v[102:103], v[124:125], v[98:99] op_sel_hi:[1,0]
	v_lshl_add_u64 v[96:97], s[28:29], 0, v[96:97]
	v_cvt_pk_bf16_f32 v102, v102, v103
	v_cvt_pk_bf16_f32 v103, v100, v101
	v_lshl_add_u64 v[96:97], v[96:97], 0, v[108:109]
	global_store_dwordx2 v[96:97], v[102:103], off
	v_pk_mul_f32 v[100:101], v[122:123], v[98:99] op_sel_hi:[1,0]
	v_pk_mul_f32 v[102:103], v[120:121], v[98:99] op_sel_hi:[1,0]
	v_pk_mul_f32 v[106:107], v[106:107], v[136:137] op_sel_hi:[1,0]
	v_cvt_pk_bf16_f32 v102, v102, v103
	v_cvt_pk_bf16_f32 v103, v100, v101
	global_store_dwordx2 v[96:97], v[102:103], off offset:32
	v_pk_mul_f32 v[100:101], v[118:119], v[98:99] op_sel_hi:[1,0]
	v_pk_mul_f32 v[102:103], v[116:117], v[98:99] op_sel_hi:[1,0]
	v_pk_mul_f32 v[104:105], v[104:105], v[136:137] op_sel_hi:[1,0]
	v_cvt_pk_bf16_f32 v102, v102, v103
	v_cvt_pk_bf16_f32 v103, v100, v101
	global_store_dwordx2 v[96:97], v[102:103], off offset:256
	ds_read2_b32 v[102:103], v247 offset0:32 offset1:48
	v_pk_mul_f32 v[100:101], v[114:115], v[98:99] op_sel_hi:[1,0]
	v_pk_mul_f32 v[98:99], v[112:113], v[98:99] op_sel_hi:[1,0]
	v_cvt_pk_bf16_f32 v104, v104, v105
	v_cvt_pk_bf16_f32 v98, v98, v99
	v_cvt_pk_bf16_f32 v99, v100, v101
	global_store_dwordx2 v[96:97], v[98:99], off offset:288
	v_lshlrev_b64 v[96:97], 11, v[176:177]
	s_waitcnt lgkmcnt(0)
	v_pk_mul_f32 v[94:95], v[94:95], v[102:103] op_sel_hi:[1,0]
	v_pk_mul_f32 v[92:93], v[92:93], v[102:103] op_sel_hi:[1,0]
	v_pk_mul_f32 v[82:83], v[82:83], v[102:103] op_sel_hi:[1,0]
	v_cvt_pk_bf16_f32 v92, v92, v93
	v_cvt_pk_bf16_f32 v93, v94, v95
	v_lshl_add_u64 v[94:95], s[28:29], 0, v[96:97]
	v_pk_mul_f32 v[80:81], v[80:81], v[102:103] op_sel_hi:[1,0]
	v_lshl_add_u64 v[94:95], v[94:95], 0, v[108:109]
	v_cvt_pk_bf16_f32 v80, v80, v81
	v_cvt_pk_bf16_f32 v81, v82, v83
	v_mov_b32_e32 v82, v103
	global_store_dwordx2 v[94:95], v[80:81], off offset:288
	v_lshlrev_b64 v[80:81], 11, v[160:161]
	v_pk_mul_f32 v[78:79], v[78:79], v[82:83] op_sel_hi:[1,0]
	v_pk_mul_f32 v[76:77], v[76:77], v[82:83] op_sel_hi:[1,0]
	v_pk_mul_f32 v[70:71], v[70:71], v[82:83] op_sel_hi:[1,0]
	v_cvt_pk_bf16_f32 v76, v76, v77
	v_cvt_pk_bf16_f32 v77, v78, v79
	v_lshl_add_u64 v[78:79], s[28:29], 0, v[80:81]
	v_pk_mul_f32 v[68:69], v[68:69], v[82:83] op_sel_hi:[1,0]
	v_lshl_add_u64 v[78:79], v[78:79], 0, v[108:109]
	v_cvt_pk_bf16_f32 v68, v68, v69
	v_cvt_pk_bf16_f32 v69, v70, v71
	global_store_dwordx2 v[78:79], v[68:69], off offset:256
	ds_read2_b32 v[68:69], v247 offset0:128 offset1:144
	v_pk_mul_f32 v[66:67], v[66:67], v[82:83] op_sel_hi:[1,0]
	v_pk_mul_f32 v[64:65], v[64:65], v[82:83] op_sel_hi:[1,0]
	v_pk_mul_f32 v[90:91], v[90:91], v[102:103] op_sel_hi:[1,0]
	v_cvt_pk_bf16_f32 v64, v64, v65
	v_cvt_pk_bf16_f32 v65, v66, v67
	global_store_dwordx2 v[78:79], v[64:65], off offset:288
	v_lshlrev_b64 v[64:65], 11, v[128:129]
	s_waitcnt lgkmcnt(0)
	v_pk_mul_f32 v[62:63], v[62:63], v[68:69] op_sel_hi:[1,0]
	v_pk_mul_f32 v[60:61], v[60:61], v[68:69] op_sel_hi:[1,0]
	v_pk_mul_f32 v[50:51], v[50:51], v[68:69] op_sel_hi:[1,0]
	v_cvt_pk_bf16_f32 v60, v60, v61
	v_cvt_pk_bf16_f32 v61, v62, v63
	v_lshl_add_u64 v[62:63], s[28:29], 0, v[64:65]
	v_pk_mul_f32 v[48:49], v[48:49], v[68:69] op_sel_hi:[1,0]
	v_lshl_add_u64 v[62:63], v[62:63], 0, v[108:109]
	v_cvt_pk_bf16_f32 v48, v48, v49
	v_cvt_pk_bf16_f32 v49, v50, v51
	v_mov_b32_e32 v50, v69
	global_store_dwordx2 v[62:63], v[48:49], off offset:288
	v_lshlrev_b64 v[48:49], 11, v[130:131]
	v_pk_mul_f32 v[46:47], v[46:47], v[50:51] op_sel_hi:[1,0]
	v_pk_mul_f32 v[44:45], v[44:45], v[50:51] op_sel_hi:[1,0]
	v_pk_mul_f32 v[38:39], v[38:39], v[50:51] op_sel_hi:[1,0]
	v_cvt_pk_bf16_f32 v44, v44, v45
	v_cvt_pk_bf16_f32 v45, v46, v47
	v_lshl_add_u64 v[46:47], s[28:29], 0, v[48:49]
	v_pk_mul_f32 v[36:37], v[36:37], v[50:51] op_sel_hi:[1,0]
	v_lshl_add_u64 v[46:47], v[46:47], 0, v[108:109]
	v_cvt_pk_bf16_f32 v36, v36, v37
	v_cvt_pk_bf16_f32 v37, v38, v39
	global_store_dwordx2 v[46:47], v[36:37], off offset:256
	ds_read2_b32 v[36:37], v247 offset0:160 offset1:176
	v_pk_mul_f32 v[34:35], v[34:35], v[50:51] op_sel_hi:[1,0]
	v_pk_mul_f32 v[32:33], v[32:33], v[50:51] op_sel_hi:[1,0]
	v_pk_mul_f32 v[88:89], v[88:89], v[102:103] op_sel_hi:[1,0]
	v_cvt_pk_bf16_f32 v32, v32, v33
	v_cvt_pk_bf16_f32 v33, v34, v35
	global_store_dwordx2 v[46:47], v[32:33], off offset:288
	v_lshlrev_b64 v[32:33], 11, v[132:133]
	s_waitcnt lgkmcnt(0)
	v_pk_mul_f32 v[30:31], v[30:31], v[36:37] op_sel_hi:[1,0]
	v_pk_mul_f32 v[28:29], v[28:29], v[36:37] op_sel_hi:[1,0]
	v_pk_mul_f32 v[18:19], v[18:19], v[36:37] op_sel_hi:[1,0]
	v_cvt_pk_bf16_f32 v28, v28, v29
	v_cvt_pk_bf16_f32 v29, v30, v31
	v_lshl_add_u64 v[30:31], s[28:29], 0, v[32:33]
	v_pk_mul_f32 v[16:17], v[16:17], v[36:37] op_sel_hi:[1,0]
	v_lshl_add_u64 v[30:31], v[30:31], 0, v[108:109]
	v_cvt_pk_bf16_f32 v16, v16, v17
	v_cvt_pk_bf16_f32 v17, v18, v19
	v_mov_b32_e32 v18, v37
	global_store_dwordx2 v[30:31], v[16:17], off offset:288
	v_lshlrev_b64 v[16:17], 11, v[134:135]
	v_pk_mul_f32 v[14:15], v[14:15], v[18:19] op_sel_hi:[1,0]
	v_pk_mul_f32 v[12:13], v[12:13], v[18:19] op_sel_hi:[1,0]
	v_pk_mul_f32 v[86:87], v[86:87], v[102:103] op_sel_hi:[1,0]
	v_pk_mul_f32 v[84:85], v[84:85], v[102:103] op_sel_hi:[1,0]
	v_pk_mul_f32 v[74:75], v[74:75], v[82:83] op_sel_hi:[1,0]
	v_pk_mul_f32 v[72:73], v[72:73], v[82:83] op_sel_hi:[1,0]
	v_pk_mul_f32 v[58:59], v[58:59], v[68:69] op_sel_hi:[1,0]
	v_pk_mul_f32 v[56:57], v[56:57], v[68:69] op_sel_hi:[1,0]
	v_pk_mul_f32 v[54:55], v[54:55], v[68:69] op_sel_hi:[1,0]
	v_pk_mul_f32 v[52:53], v[52:53], v[68:69] op_sel_hi:[1,0]
	v_pk_mul_f32 v[42:43], v[42:43], v[50:51] op_sel_hi:[1,0]
	v_pk_mul_f32 v[40:41], v[40:41], v[50:51] op_sel_hi:[1,0]
	v_pk_mul_f32 v[26:27], v[26:27], v[36:37] op_sel_hi:[1,0]
	v_pk_mul_f32 v[24:25], v[24:25], v[36:37] op_sel_hi:[1,0]
	v_pk_mul_f32 v[22:23], v[22:23], v[36:37] op_sel_hi:[1,0]
	v_pk_mul_f32 v[20:21], v[20:21], v[36:37] op_sel_hi:[1,0]
	v_cvt_pk_bf16_f32 v12, v12, v13
	v_cvt_pk_bf16_f32 v13, v14, v15
	v_lshl_add_u64 v[14:15], s[28:29], 0, v[16:17]
	v_pk_mul_f32 v[10:11], v[10:11], v[18:19] op_sel_hi:[1,0]
	v_pk_mul_f32 v[8:9], v[8:9], v[18:19] op_sel_hi:[1,0]
	v_pk_mul_f32 v[6:7], v[6:7], v[18:19] op_sel_hi:[1,0]
	v_pk_mul_f32 v[4:5], v[4:5], v[18:19] op_sel_hi:[1,0]
	v_pk_mul_f32 v[2:3], v[2:3], v[18:19] op_sel_hi:[1,0]
	v_pk_mul_f32 v[0:1], v[0:1], v[18:19] op_sel_hi:[1,0]
	v_cvt_pk_bf16_f32 v105, v106, v107
	v_cvt_pk_bf16_f32 v88, v88, v89
	v_cvt_pk_bf16_f32 v89, v90, v91
	v_cvt_pk_bf16_f32 v84, v84, v85
	v_cvt_pk_bf16_f32 v85, v86, v87
	v_cvt_pk_bf16_f32 v72, v72, v73
	v_cvt_pk_bf16_f32 v73, v74, v75
	v_cvt_pk_bf16_f32 v56, v56, v57
	v_cvt_pk_bf16_f32 v57, v58, v59
	v_cvt_pk_bf16_f32 v52, v52, v53
	v_cvt_pk_bf16_f32 v53, v54, v55
	v_cvt_pk_bf16_f32 v40, v40, v41
	v_cvt_pk_bf16_f32 v41, v42, v43
	v_cvt_pk_bf16_f32 v24, v24, v25
	v_cvt_pk_bf16_f32 v25, v26, v27
	v_cvt_pk_bf16_f32 v20, v20, v21
	v_cvt_pk_bf16_f32 v21, v22, v23
	v_lshl_add_u64 v[14:15], v[14:15], 0, v[108:109]
	v_cvt_pk_bf16_f32 v8, v8, v9
	v_cvt_pk_bf16_f32 v9, v10, v11
	v_cvt_pk_bf16_f32 v4, v4, v5
	v_cvt_pk_bf16_f32 v5, v6, v7
	v_cvt_pk_bf16_f32 v0, v0, v1
	v_cvt_pk_bf16_f32 v1, v2, v3
	global_store_dwordx2 v[110:111], v[140:141], off
	global_store_dwordx2 v[110:111], v[104:105], off offset:32
	global_store_dwordx2 v[94:95], v[92:93], off
	global_store_dwordx2 v[94:95], v[88:89], off offset:32
	global_store_dwordx2 v[94:95], v[84:85], off offset:256
	global_store_dwordx2 v[78:79], v[76:77], off
	global_store_dwordx2 v[78:79], v[72:73], off offset:32
	global_store_dwordx2 v[62:63], v[60:61], off
	global_store_dwordx2 v[62:63], v[56:57], off offset:32
	global_store_dwordx2 v[62:63], v[52:53], off offset:256
	global_store_dwordx2 v[46:47], v[44:45], off
	global_store_dwordx2 v[46:47], v[40:41], off offset:32
	global_store_dwordx2 v[30:31], v[28:29], off
	global_store_dwordx2 v[30:31], v[24:25], off offset:32
	global_store_dwordx2 v[30:31], v[20:21], off offset:256
	global_store_dwordx2 v[14:15], v[12:13], off
	global_store_dwordx2 v[14:15], v[8:9], off offset:32
	global_store_dwordx2 v[14:15], v[4:5], off offset:256
	global_store_dwordx2 v[14:15], v[0:1], off offset:288
